# FoX unit start: the work-queue atomic returns straight into the unext register and is only waited for at the unit end (was a full vmcnt(0) stall before the unit's first loads)
# speedup vs baseline: 1.0070x; 1.0068x over previous
; template <int VAR>
; __device__ __forceinline__ void fox_attn_phase(const bf16* QKV, const float* CUM, const float* KPART, bf16* AO, int* JST, unsigned* Q, LAS unsigned char* lds, int vcu, int G) {
;     ...
;         int unext = 0;
;         if (tid == 0) unext = (int)__hip_atomic_fetch_add(Q, 1u, __ATOMIC_RELAXED, __HIP_MEMORY_SCOPE_AGENT);
;         const int bh = (ui & 255) >> 2, qb = 31 - (4 * (ui >> 8) + (ui & 3));
;         const int b = bh >> 5, h = bh & 31;
;         const int q0 = qb * 256, R = q0 + wave * 32, qpos = R + r32;
;         const size_t tok = (size_t)b * SEQ + qpos;
;         const bf16* Qp = QKV + tok * N_FOX_MAIN + h * 64 + hi * 8;
;         bf16x8 qr[4]; float qn2 = 0.f;
; #pragma unroll
;         for (int d0 = 0; d0 < 4; ++d0) { const v4u w = *(const v4u*)(Qp + d0 * 16); const unsigned ww[4] = {w.x, w.y, w.z, w.w};
; #pragma unroll
;             for (int e = 0; e < 4; ++e) { const float x0 = bf2f((unsigned short)(ww[e] & 0xffffu)), x1 = bf2f((unsigned short)(ww[e] >> 16)); qn2 += x0 * x0 + x1 * x1; }
;             qr[d0] = scale_q(w); }
;         qn2 += __shfl_xor(qn2, 32);
;         const float4 kp = *(const float4*)(KPART + bh * 4);
;         const float kmax = fmaxf(fmaxf(kp.x, kp.y), fmaxf(kp.z, kp.w)) * 1.001f;
;         const float qk_bound = 0.125f * sqrtf(qn2) * 1.001f * kmax;
;         const float* cum = CUM + (size_t)bh * SEQ;
;         const float cref = cum[q0];
;         f32x16 o[2];
; #pragma unroll
;         for (int r = 0; r < 16; ++r) { o[0][r] = 0.f; o[1][r] = 0.f; }
;         float m = -INFINITY, l = 0.f;
;         const int jmax = 4 * qb + 3, jw = (R + 31) >> 6;
;         int jstop = -1;
;         const int colkv = (tid < 256 ? 2048 : 4096) + h * 64 + (tid & 7) * 8;
;         const bf16* gA = QKV + ((size_t)b * SEQ + rowA) * N_FOX_MAIN + colkv;
;         const bf16* gB = QKV + ((size_t)b * SEQ + rowB) * N_FOX_MAIN + colkv;
;         const bool brole = (tid >= 256 && tid < 320);
;         v4u ra = *(const v4u*)(gA + (size_t)jmax * 64 * N_FOX_MAIN), rb = *(const v4u*)(gB + (size_t)jmax * 64 * N_FOX_MAIN);
;         float breg = brole ? cum[jmax * 64 + (tid - 256)] : 0.f;
.LBB0_182:
	v_mov_b32_e32 v169, 0
	s_and_saveexec_b64 s[18:19], s[42:43]
	s_cbranch_execz .LBB0_186
	s_mov_b64 s[22:23], exec
	v_mbcnt_lo_u32_b32 v0, s22, 0
	v_mbcnt_hi_u32_b32 v0, s23, v0
	v_cmp_eq_u32_e32 vcc, 0, v0
	s_and_saveexec_b64 s[20:21], vcc
	s_cbranch_execz .LBB0_185
	s_bcnt1_i32_b64 s22, s[22:23]
	v_mov_b32_e32 v2, s22
	global_atomic_add v169, v1, v2, s[16:17] sc0
.LBB0_185:
	s_or_b64 exec, exec, s[20:21]
.LBB0_186:
	s_or_b64 exec, exec, s[18:19]
	s_ashr_i32 s31, s28, 6
	s_and_b32 s18, s31, -4
	s_and_b32 s29, s28, 3
	s_or_b32 s18, s18, s29
	s_sub_i32 s50, 31, s18
	s_lshl_b32 s22, s50, 8
	s_add_i32 s25, s22, s24
	v_or_b32_e32 v134, s25, v142
	s_lshl_b32 s18, s28, 6
	s_and_b32 s84, s18, 0x2000
	v_ashrrev_i32_e32 v135, 31, v134
	v_lshl_add_u64 v[136:137], v[134:135], 0, s[84:85]
	v_mov_b64_e32 v[2:3], s[12:13]
	v_mad_u64_u32 v[4:5], s[18:19], v136, s36, v[2:3]
	s_lshl_b32 s18, s28, 4
	s_and_b32 s20, s18, 0x7c0
	v_mad_i32_i24 v5, v137, s36, v5
	s_lshl_b32 s18, s20, 1
	s_mov_b32 s19, s85
	v_lshl_add_u64 v[4:5], v[4:5], 0, s[18:19]
	v_mov_b32_e32 v131, v1
	v_lshl_add_u64 v[4:5], v[4:5], 0, v[130:131]
	global_load_dwordx4 v[14:17], v[4:5], off
	global_load_dwordx4 v[18:21], v[4:5], off offset:32
	global_load_dwordx4 v[38:41], v[4:5], off offset:64
	global_load_dwordx4 v[42:45], v[4:5], off offset:96
	s_bfe_u32 s19, s28, 0x60002
	s_lshl_b32 s21, s19, 4
	v_lshl_add_u64 v[4:5], s[84:85], 0, v[122:123]
	v_lshl_add_u64 v[6:7], s[84:85], 0, v[124:125]
	s_lshl_b32 s19, s19, 15
	v_mov_b32_e32 v12, s21
	v_or_b32_e32 v0, s20, v144
	v_mad_u64_u32 v[8:9], s[20:21], v4, s36, v[2:3]
	v_mad_u64_u32 v[2:3], s[20:21], v6, s36, v[2:3]
	s_mov_b32 s23, s85
	s_add_u32 s20, s52, s19
	s_addc_u32 s21, s53, 0
	s_lshl_b64 s[22:23], s[22:23], 2
	s_add_u32 s22, s20, s22
	v_lshlrev_b32_e32 v0, 1, v0
	v_mad_i32_i24 v9, v5, s36, v9
	v_mad_i32_i24 v3, v7, s36, v3
	s_addc_u32 s23, s21, s23
	s_lshl_b32 s57, s50, 2
	v_lshl_add_u64 v[138:139], v[8:9], 0, v[0:1]
	v_lshl_add_u64 v[140:141], v[2:3], 0, v[0:1]
	s_or_b32 s69, s57, 3
	v_mad_u64_u32 v[6:7], s[50:51], s69, v195, v[138:139]
	v_mad_u64_u32 v[10:11], s[50:51], s69, v195, v[140:141]
	global_load_dwordx4 v[2:5], v12, s[8:9]
	s_nop 0
	global_load_dwordx4 v[6:9], v[6:7], off
	s_nop 0
	global_load_dword v131, v1, s[22:23]
	s_nop 0
	global_load_dwordx4 v[10:13], v[10:11], off
	s_lshl_b32 s84, s69, 6
	v_mov_b32_e32 v133, 0
	s_waitcnt vmcnt(7)
	v_lshlrev_b32_e32 v36, 16, v14
	v_and_b32_e32 v37, 0xffff0000, v14
	v_lshlrev_b32_e32 v34, 16, v15
	v_and_b32_e32 v35, 0xffff0000, v15
	v_lshlrev_b32_e32 v32, 16, v16
	v_and_b32_e32 v33, 0xffff0000, v16
	v_pk_mul_f32 v[46:47], v[36:37], v[36:37]
	v_pk_mul_f32 v[48:49], v[34:35], v[34:35]
	v_lshlrev_b32_e32 v30, 16, v17
	v_and_b32_e32 v31, 0xffff0000, v17
	v_pk_mul_f32 v[50:51], v[32:33], v[32:33]
	v_add_f32_e32 v48, v48, v49
	v_add_f32_e32 v46, v46, v47
	s_waitcnt vmcnt(6)
	v_lshlrev_b32_e32 v28, 16, v18
	v_and_b32_e32 v29, 0xffff0000, v18
	v_pk_mul_f32 v[52:53], v[30:31], v[30:31]
	v_add_f32_e32 v46, v46, v48
	v_add_f32_e32 v47, v50, v51
	v_lshlrev_b32_e32 v26, 16, v19
	v_and_b32_e32 v27, 0xffff0000, v19
	v_pk_mul_f32 v[54:55], v[28:29], v[28:29]
	v_add_f32_e32 v0, v52, v53
	v_add_f32_e32 v46, v47, v46
	v_lshlrev_b32_e32 v24, 16, v20
	v_and_b32_e32 v25, 0xffff0000, v20
	v_pk_mul_f32 v[56:57], v[26:27], v[26:27]
	v_add_f32_e32 v0, v0, v46
	v_add_f32_e32 v46, v54, v55
	v_lshlrev_b32_e32 v22, 16, v21
	v_and_b32_e32 v23, 0xffff0000, v21
	v_pk_mul_f32 v[58:59], v[24:25], v[24:25]
	v_add_f32_e32 v0, v46, v0
	v_add_f32_e32 v46, v56, v57
	s_waitcnt vmcnt(5)
	v_lshlrev_b32_e32 v20, 16, v38
	v_and_b32_e32 v21, 0xffff0000, v38
	v_pk_mul_f32 v[60:61], v[22:23], v[22:23]
	v_add_f32_e32 v0, v46, v0
	v_add_f32_e32 v46, v58, v59
	v_lshlrev_b32_e32 v18, 16, v39
	v_and_b32_e32 v19, 0xffff0000, v39
	v_pk_mul_f32 v[62:63], v[20:21], v[20:21]
	v_add_f32_e32 v0, v46, v0
	v_add_f32_e32 v46, v60, v61
	v_lshlrev_b32_e32 v16, 16, v40
	v_and_b32_e32 v17, 0xffff0000, v40
	v_pk_mul_f32 v[64:65], v[18:19], v[18:19]
	v_add_f32_e32 v0, v46, v0
	v_add_f32_e32 v46, v62, v63
	v_lshlrev_b32_e32 v14, 16, v41
	v_and_b32_e32 v15, 0xffff0000, v41
	v_pk_mul_f32 v[66:67], v[16:17], v[16:17]
	v_add_f32_e32 v0, v46, v0
	v_add_f32_e32 v46, v64, v65
	v_pk_mul_f32 v[68:69], v[14:15], v[14:15]
	s_waitcnt vmcnt(4)
	v_lshlrev_b32_e32 v38, 16, v42
	v_and_b32_e32 v39, 0xffff0000, v42
	v_add_f32_e32 v0, v46, v0
	v_add_f32_e32 v46, v66, v67
	v_pk_mul_f32 v[70:71], v[38:39], v[38:39]
	v_lshlrev_b32_e32 v40, 16, v43
	v_and_b32_e32 v41, 0xffff0000, v43
	v_add_f32_e32 v0, v46, v0
	v_add_f32_e32 v46, v68, v69
	v_pk_mul_f32 v[72:73], v[40:41], v[40:41]
	v_lshlrev_b32_e32 v42, 16, v44
	v_and_b32_e32 v43, 0xffff0000, v44
	v_add_f32_e32 v0, v46, v0
	v_add_f32_e32 v46, v70, v71
	v_pk_mul_f32 v[74:75], v[42:43], v[42:43]
	v_lshlrev_b32_e32 v44, 16, v45
	v_and_b32_e32 v45, 0xffff0000, v45
	v_add_f32_e32 v0, v46, v0
	v_add_f32_e32 v46, v72, v73
	v_pk_mul_f32 v[76:77], v[44:45], v[44:45]
	v_add_f32_e32 v0, v46, v0
	v_add_f32_e32 v46, v74, v75
	v_add_f32_e32 v0, v46, v0
	v_add_f32_e32 v46, v76, v77
	v_add_f32_e32 v47, v46, v0
	ds_bpermute_b32 v48, v143, v47
	s_and_saveexec_b64 s[22:23], s[44:45]
	s_cbranch_execz .LBB0_188
	v_or_b32_e32 v0, s84, v129
	v_lshl_add_u64 v[50:51], v[0:1], 2, s[20:21]
	global_load_dword v133, v[50:51], off
